# diff attention main loop: scalar slot copies removed (K addresses formed from the slot registers directly), the two waits before each step barrier merged into one, pads before the first PV MFMA droppe
# speedup vs baseline: 1.0031x; 1.0020x over previous
; __device__ __forceinline__ unsigned cvtpk(float lo, float hi) { unsigned r; asm volatile("v_cvt_pk_bf16_f32 %0, %1, %2" : "=v"(r) : "v"(lo), "v"(hi)); return r; }
; __device__ __forceinline__ void finishSM(f32x16& p0, f32x16& p1, float alpha, float& l_reg, bf16x8& pa0, bf16x8& pa1, bf16x8& pa2, bf16x8& pa3) {
; #pragma unroll
;   for (int r = 0; r < 16; ++r) p1[r] = __builtin_amdgcn_exp2f(p1[r]);
;   float ps = 0;
; #pragma unroll
;   for (int r = 0; r < 16; ++r) ps += p0[r];
; #pragma unroll
;   for (int r = 0; r < 16; ++r) ps += p1[r];
;   { auto rr = __builtin_amdgcn_permlane32_swap(__float_as_uint(ps), __float_as_uint(ps), false, false);
;     ps = __uint_as_float(rr[0]) + __uint_as_float(rr[1]); }
;   l_reg = l_reg * alpha + ps;
;     ...
;   PK4(p0, 0, pa0); PK4(p0, 8, pa1); PK4(p1, 0, pa2); PK4(p1, 8, pa3);
;     ...
; }
; __device__ __forceinline__ bf16x8 scale_bf16x8(bf16x8 v, float c) {
;   u32x4 w = *reinterpret_cast<u32x4*>(&v), o;
; #pragma unroll
;   for (int i = 0; i < 4; ++i) { const float lo = __uint_as_float(w[i] << 16), hh = __uint_as_float(w[i] & 0xffff0000u); o[i] = cvtpk(lo * c, hh * c); }
;   return *reinterpret_cast<bf16x8*>(&o);
; }
; template <int ND0> __device__ __forceinline__ void qkt(f32x16& p0, f32x16& p1, const char* Ks, const bf16x8* qr, int r32, int hi, int cboff, const f32x16& ci) {
; #pragma unroll
;   for (int d0 = 0; d0 < ND0; ++d0) { int cb = cboff + (d0 * 16 + hi * 8) * 2;
;     bf16x8 b0 = *reinterpret_cast<const bf16x8*>(Ks + KSWZ(r32, cb));
;     bf16x8 b1 = *reinterpret_cast<const bf16x8*>(Ks + KSWZ(32 + r32, cb));
;     if (d0 == 0) { p0 = __builtin_amdgcn_mfma_f32_32x32x16_bf16(b0, qr[0], ci, 0, 0, 0); p1 = __builtin_amdgcn_mfma_f32_32x32x16_bf16(b1, qr[0], ci, 0, 0, 0); }
;     else { p0 = __builtin_amdgcn_mfma_f32_32x32x16_bf16(b0, qr[d0], p0, 0, 0, 0); p1 = __builtin_amdgcn_mfma_f32_32x32x16_bf16(b1, qr[d0], p1, 0, 0, 0); } }
; }
.LBB0_166:
	v_add_u32_e32 v96, s68, v188
	ds_read_b128 v[210:213], v96 offset:24576
	ds_read_b128 v[96:99], v96 offset:16384
	v_add_u32_e32 v201, s68, v196
	v_exp_f32_e32 v206, v81
	v_exp_f32_e32 v207, v82
	v_exp_f32_e32 v208, v83
	s_waitcnt lgkmcnt(0)
	v_mfma_f32_32x32x16_bf16 v[112:127], v[96:99], v[128:131], v[64:79]
	v_exp_f32_e32 v209, v84
	v_exp_f32_e32 v87, v87
	v_exp_f32_e32 v214, v88
	v_exp_f32_e32 v220, v93
	v_exp_f32_e32 v221, v94
	v_exp_f32_e32 v95, v95
	v_mfma_f32_32x32x16_bf16 v[96:111], v[210:213], v[128:131], v[64:79]
	ds_read_b128 v[210:213], v201 offset:24576
	ds_read_b128 v[216:219], v201 offset:16384
	v_add_u32_e32 v201, s68, v190
	s_waitcnt lgkmcnt(0)
	v_mfma_f32_32x32x16_bf16 v[112:127], v[216:219], v[132:135], v[112:127]
	v_mfma_f32_32x32x16_bf16 v[96:111], v[210:213], v[132:135], v[96:111]
	ds_read_b128 v[210:213], v201 offset:24576
	ds_read_b128 v[216:219], v201 offset:16384
	v_add_u32_e32 v201, s68, v189
	s_waitcnt lgkmcnt(0)
	v_mfma_f32_32x32x16_bf16 v[112:127], v[216:219], v[136:139], v[112:127]
	v_mfma_f32_32x32x16_bf16 v[96:111], v[210:213], v[136:139], v[96:111]
	ds_read_b128 v[210:213], v201 offset:24576
	ds_read_b128 v[216:219], v201 offset:16384
	v_exp_f32_e32 v201, v80
	v_pk_add_f32 v[144:145], v[160:161], v[162:163]
	v_pk_add_f32 v[144:145], v[144:145], v[164:165]
	v_pk_add_f32 v[144:145], v[144:145], v[166:167]
	v_pk_add_f32 v[144:145], v[144:145], v[168:169]
	v_pk_add_f32 v[144:145], v[144:145], v[170:171]
	v_pk_add_f32 v[144:145], v[144:145], v[172:173]
	v_pk_add_f32 v[144:145], v[144:145], v[174:175]
	v_pk_add_f32 v[144:145], v[144:145], v[206:207]
	v_pk_add_f32 v[144:145], v[144:145], v[208:209]
	v_pk_add_f32 v[144:145], v[144:145], v[220:221]
	v_add_f32_e32 v80, v87, v214
	v_add_f32_e32 v80, v95, v80
	s_waitcnt lgkmcnt(1)
	v_mfma_f32_32x32x16_bf16 v[96:111], v[210:213], v[140:143], v[96:111]
	v_exp_f32_e32 v212, v85
	v_add_f32_e32 v80, v201, v80
	v_exp_f32_e32 v213, v86
	s_waitcnt lgkmcnt(0)
	v_mfma_f32_32x32x16_bf16 v[112:127], v[216:219], v[140:143], v[112:127]
	v_exp_f32_e32 v216, v89
	v_exp_f32_e32 v217, v90
	v_exp_f32_e32 v218, v91
	v_exp_f32_e32 v219, v92
	v_pk_add_f32 v[144:145], v[144:145], v[212:213]
	v_pk_add_f32 v[144:145], v[144:145], v[216:217]
	v_pk_add_f32 v[144:145], v[144:145], v[218:219]
	v_add_f32_e32 v80, v144, v80
	v_add_f32_e32 v210, v145, v80
	v_cvt_pk_bf16_f32 v80, v173, v175
	v_cvt_pk_bf16_f32 v81, v171, v174
	v_cvt_pk_bf16_f32 v82, v169, v172
	v_cvt_pk_bf16_f32 v83, v168, v170
	v_cvt_pk_bf16_f32 v88, v165, v167
	v_cvt_pk_bf16_f32 v89, v163, v166
	v_cvt_pk_bf16_f32 v90, v161, v164
	v_cvt_pk_bf16_f32 v91, v160, v162
	v_cvt_pk_bf16_f32 v84, v201, v206
	v_cvt_pk_bf16_f32 v85, v207, v208
	v_cvt_pk_bf16_f32 v86, v209, v212
	v_cvt_pk_bf16_f32 v87, v213, v87
	v_cvt_pk_bf16_f32 v92, v214, v216
	v_cvt_pk_bf16_f32 v93, v217, v218
	v_cvt_pk_bf16_f32 v94, v219, v220
	v_cvt_pk_bf16_f32 v95, v221, v95
	s_andn2_b64 vcc, exec, s[10:11]
	v_add_u32_e32 v212, s56, v202
	s_cbranch_vccnz .LBB0_168
	v_add_u32_e32 v160, 0xc0, v212
	v_med3_i32 v161, v160, 0, v249
	v_med3_i32 v160, v160, s75, v250
	v_lshl_add_u32 v162, v160, 2, s69
	v_add_u32_e32 v160, 0xc1, v212
	v_med3_i32 v163, v160, 0, v249
	v_med3_i32 v160, v160, s75, v250
	v_lshl_add_u32 v164, v160, 2, s69
	v_add_u32_e32 v160, 0xc2, v212
	v_med3_i32 v165, v160, 0, v249
	v_med3_i32 v160, v160, s75, v250
	v_lshl_add_u32 v166, v160, 2, s69
	v_add_u32_e32 v160, 0xc3, v212
	v_med3_i32 v167, v160, 0, v249
	v_med3_i32 v160, v160, s75, v250
	v_lshl_add_u32 v161, v161, 2, s69
	v_lshl_add_u32 v163, v163, 2, s69
	v_lshl_add_u32 v165, v165, 2, s69
	v_lshl_add_u32 v167, v167, 2, s69
	v_lshl_add_u32 v168, v160, 2, s69
	ds_read_b32 v160, v161
	ds_read_b32 v162, v162 offset:128
	ds_read_b32 v161, v163
	ds_read_b32 v163, v164 offset:128
	ds_read_b32 v164, v165
	ds_read_b32 v166, v166 offset:128
	ds_read_b32 v165, v167
	ds_read_b32 v167, v168 offset:128
	v_add_u32_e32 v168, 0xc8, v212
	v_med3_i32 v169, v168, 0, v249
	v_med3_i32 v168, v168, s75, v250
	v_lshl_add_u32 v170, v168, 2, s69
	v_add_u32_e32 v168, 0xc9, v212
	v_med3_i32 v171, v168, 0, v249
	v_med3_i32 v168, v168, s75, v250
	v_lshl_add_u32 v172, v168, 2, s69
	v_add_u32_e32 v168, 0xca, v212
	v_med3_i32 v173, v168, 0, v249
	v_med3_i32 v168, v168, s75, v250
	v_add_u32_e32 v207, 0xd1, v212
	v_lshl_add_u32 v174, v168, 2, s69
	v_add_u32_e32 v168, 0xcb, v212
	v_med3_i32 v208, v207, 0, v249
	v_med3_i32 v207, v207, s75, v250
	v_med3_i32 v175, v168, 0, v249
	v_med3_i32 v168, v168, s75, v250
	v_lshl_add_u32 v213, v207, 2, s69
	v_add_u32_e32 v207, 0xd2, v212
	v_lshl_add_u32 v169, v169, 2, s69
	v_lshl_add_u32 v171, v171, 2, s69
	v_lshl_add_u32 v173, v173, 2, s69
	v_lshl_add_u32 v175, v175, 2, s69
	v_lshl_add_u32 v201, v168, 2, s69
	v_lshl_add_u32 v209, v208, 2, s69
	v_med3_i32 v208, v207, 0, v249
	v_med3_i32 v207, v207, s75, v250
	ds_read_b32 v168, v169
	ds_read_b32 v170, v170 offset:128
	ds_read_b32 v169, v171
	ds_read_b32 v171, v172 offset:128
	ds_read_b32 v172, v173
	ds_read_b32 v174, v174 offset:128
	ds_read_b32 v173, v175
	ds_read_b32 v175, v201 offset:128
	v_add_u32_e32 v201, 0xd0, v212
	v_lshl_add_u32 v217, v207, 2, s69
	v_add_u32_e32 v207, 0xd3, v212
	v_med3_i32 v206, v201, 0, v249
	v_lshl_add_u32 v214, v208, 2, s69
	v_med3_i32 v208, v207, 0, v249
	v_med3_i32 v201, v201, s75, v250
	v_lshl_add_u32 v206, v206, 2, s69
	v_med3_i32 v207, v207, s75, v250
	v_lshl_add_u32 v219, v208, 2, s69
	v_lshl_add_u32 v201, v201, 2, s69
	v_lshl_add_u32 v220, v207, 2, s69
	ds_read_b32 v206, v206
	ds_read_b32 v208, v201 offset:128
	ds_read_b32 v207, v209
	ds_read_b32 v209, v213 offset:128
	ds_read_b32 v216, v214
	ds_read_b32 v218, v217 offset:128
	ds_read_b32 v217, v219
	ds_read_b32 v219, v220 offset:128
	v_add_u32_e32 v214, 0xd9, v212
	v_med3_i32 v220, v214, 0, v249
	v_lshl_add_u32 v221, v220, 2, s69
	v_add_u32_e32 v220, 0xda, v212
	v_med3_i32 v222, v220, 0, v249
	v_med3_i32 v220, v220, s75, v250
	v_add_u32_e32 v201, 0xd8, v212
	v_lshl_add_u32 v226, v220, 2, s69
	v_add_u32_e32 v220, 0xdb, v212
	v_med3_i32 v213, v201, 0, v249
	v_lshl_add_u32 v223, v222, 2, s69
	v_med3_i32 v222, v220, 0, v249
	v_med3_i32 v220, v220, s75, v250
	v_med3_i32 v201, v201, s75, v250
	v_lshl_add_u32 v213, v213, 2, s69
	v_med3_i32 v214, v214, s75, v250
	v_lshl_add_u32 v225, v222, 2, s69
	v_lshl_add_u32 v227, v220, 2, s69
	v_lshl_add_u32 v201, v201, 2, s69
	v_lshl_add_u32 v214, v214, 2, s69
	ds_read_b32 v220, v213
	ds_read_b32 v222, v201 offset:128
	ds_read_b32 v224, v223
	ds_read_b32 v225, v225
	ds_read_b32 v221, v221
	ds_read_b32 v227, v227 offset:128
	ds_read_b32 v226, v226 offset:128
	ds_read_b32 v223, v214 offset:128
	s_waitcnt lgkmcnt(4)
; #define SBAR() __builtin_amdgcn_sched_barrier(0)
; __device__ __forceinline__ float max3f(float a, float b, float c) { float r; asm("v_max3_f32 %0, %1, %2, %3" : "=v"(r) : "v"(a), "v"(b), "v"(c)); return r; }
; #define VRD8(D0, L0, H0, L1, H1, L2, H2, L3, H3) do { L0 = tr_read<v_rd_off(D0, 0, 0)>(vb); H0 = tr_read<v_rd_off(D0, 0, 1)>(vb); L1 = tr_read<v_rd_off(D0, 1, 0)>(vb); H1 = tr_read<v_rd_off(D0, 1, 1)>(vb); \
;     L2 = tr_read<v_rd_off(D0, 2, 0)>(vb); H2 = tr_read<v_rd_off(D0, 2, 1)>(vb); L3 = tr_read<v_rd_off(D0, 3, 0)>(vb); H3 = tr_read<v_rd_off(D0, 3, 1)>(vb); } while (0)
; #define MMA4(OD, L0, H0, L1, H1, L2, H2, L3, H3) do { OD = __builtin_amdgcn_mfma_f32_32x32x16_bf16(pa0, PK(L0, H0), OD, 0, 0, 0); OD = __builtin_amdgcn_mfma_f32_32x32x16_bf16(pa1, PK(L1, H1), OD, 0, 0, 0); \
;     OD = __builtin_amdgcn_mfma_f32_32x32x16_bf16(pa2, PK(L2, H2), OD, 0, 0, 0); OD = __builtin_amdgcn_mfma_f32_32x32x16_bf16(pa3, PK(L3, H3), OD, 0, 0, 0); } while (0)
; __device__ __forceinline__ void pv_partial(f32x16* o, int vb, bf16x8 pa0, bf16x8 pa1, bf16x8 pa2, bf16x8 pa3, f32x16& p0, f32x16& p1, float& m_ref, f32x16& negm, float& alpha) {
;   s16x4 a0, a1, a2, a3, a4, a5, a6, a7, b0, b1, b2, b3, b4, b5, b6, b7;
;   VRD8(0, a0, a1, a2, a3, a4, a5, a6, a7);
;   VRD8(1, b0, b1, b2, b3, b4, b5, b6, b7);
;   asm volatile("s_waitcnt lgkmcnt(8)" ::: "memory"); SBAR();
;   MMA4(o[0], a0, a1, a2, a3, a4, a5, a6, a7);
;   float pmax = max3f(p0[0], p0[1], p1[0]), pmb = max3f(p0[2], p0[3], p1[1]);
;   pmax = max3f(pmax, p1[2], p1[3]);
; #pragma unroll
;   for (int r = 4; r < 16; r += 4) { pmax = max3f(pmax, p0[r], p0[r + 1]); pmb = max3f(pmb, p0[r + 2], p0[r + 3]); pmax = max3f(pmax, p1[r], p1[r + 1]); pmb = max3f(pmb, p1[r + 2], p1[r + 3]); }
;   pmax = max3f(pmax, pmb, pmb);
;   SBAR();
;   VRD8(2, a0, a1, a2, a3, a4, a5, a6, a7);
;   asm volatile("s_waitcnt lgkmcnt(8)" ::: "memory"); SBAR();
;   MMA4(o[1], b0, b1, b2, b3, b4, b5, b6, b7);
;   { auto rr = __builtin_amdgcn_permlane32_swap(__float_as_uint(pmax), __float_as_uint(pmax), false, false);
;     pmax = fmaxf(__uint_as_float(rr[0]), __uint_as_float(rr[1])); }
;   alpha = 1.f;
;   if (!__builtin_expect(__all(pmax <= THR), 1)) {
	v_pk_add_f32 v[126:127], v[126:127], v[224:225]
	s_waitcnt lgkmcnt(3)
	v_pk_add_f32 v[124:125], v[124:125], v[220:221]
	v_pk_add_f32 v[122:123], v[122:123], v[216:217]
	v_pk_add_f32 v[120:121], v[120:121], v[206:207]
	v_pk_add_f32 v[118:119], v[118:119], v[172:173]
	v_pk_add_f32 v[116:117], v[116:117], v[168:169]
	v_pk_add_f32 v[114:115], v[114:115], v[164:165]
	v_pk_add_f32 v[112:113], v[112:113], v[160:161]
	s_waitcnt lgkmcnt(1)
	v_pk_add_f32 v[110:111], v[110:111], v[226:227]
	s_waitcnt lgkmcnt(0)
	v_pk_add_f32 v[108:109], v[108:109], v[222:223]
	v_pk_add_f32 v[106:107], v[106:107], v[218:219]
	v_pk_add_f32 v[104:105], v[104:105], v[208:209]
	v_pk_add_f32 v[102:103], v[102:103], v[174:175]
	v_pk_add_f32 v[100:101], v[100:101], v[170:171]
	v_pk_add_f32 v[98:99], v[98:99], v[166:167]
	v_pk_add_f32 v[96:97], v[96:97], v[162:163]
.LBB0_168:
	v_add_u32_e32 v201, s43, v199
	ds_read_b64_tr_b16 v[160:161], v201 offset:0
	ds_read_b64_tr_b16 v[162:163], v201 offset:0x800
	ds_read_b64_tr_b16 v[164:165], v201 offset:0x1000
	ds_read_b64_tr_b16 v[166:167], v201 offset:0x1800
	ds_read_b64_tr_b16 v[168:169], v201 offset:0x2000
	ds_read_b64_tr_b16 v[170:171], v201 offset:0x2800
	ds_read_b64_tr_b16 v[172:173], v201 offset:0x3000
	ds_read_b64_tr_b16 v[174:175], v201 offset:0x3800
	ds_read_b64_tr_b16 v[216:217], v201 offset:0x200
	ds_read_b64_tr_b16 v[218:219], v201 offset:0xa00
	ds_read_b64_tr_b16 v[220:221], v201 offset:0x1200
	ds_read_b64_tr_b16 v[222:223], v201 offset:0x1a00
	ds_read_b64_tr_b16 v[224:225], v201 offset:0x2200
	ds_read_b64_tr_b16 v[226:227], v201 offset:0x2a00
	ds_read_b64_tr_b16 v[228:229], v201 offset:0x3200
	ds_read_b64_tr_b16 v[230:231], v201 offset:0x3a00
	s_waitcnt lgkmcnt(8)
	v_mfma_f32_32x32x16_bf16 v[0:15], v[80:83], v[160:163], v[0:15]
	v_max3_f32 v160, v112, v113, v96
	v_max3_f32 v161, v114, v115, v97
	v_max3_f32 v160, v160, v98, v99
	v_max3_f32 v161, v161, v118, v119
	v_max3_f32 v160, v160, v116, v117
	v_mfma_f32_32x32x16_bf16 v[0:15], v[88:91], v[164:167], v[0:15]
	v_max3_f32 v160, v160, v100, v101
	v_max3_f32 v161, v161, v102, v103
	v_max3_f32 v160, v160, v120, v121
	v_max3_f32 v161, v161, v122, v123
	v_max3_f32 v160, v160, v104, v105
	v_mfma_f32_32x32x16_bf16 v[0:15], v[84:87], v[168:171], v[0:15]
	v_max3_f32 v161, v161, v106, v107
	v_max3_f32 v160, v160, v124, v125
	v_max3_f32 v161, v161, v126, v127
	v_max3_f32 v160, v160, v108, v109
	v_max3_f32 v161, v161, v110, v111
	v_mfma_f32_32x32x16_bf16 v[0:15], v[92:95], v[172:175], v[0:15]
	v_max3_f32 v206, v160, v161, v161
	ds_read_b64_tr_b16 v[172:173], v201 offset:0x400
	ds_read_b64_tr_b16 v[174:175], v201 offset:0xc00
	ds_read_b64_tr_b16 v[168:169], v201 offset:0x1400
	ds_read_b64_tr_b16 v[170:171], v201 offset:0x1c00
	ds_read_b64_tr_b16 v[164:165], v201 offset:0x2400
	ds_read_b64_tr_b16 v[166:167], v201 offset:0x2c00
	ds_read_b64_tr_b16 v[160:161], v201 offset:0x3400
	ds_read_b64_tr_b16 v[162:163], v201 offset:0x3c00
	s_waitcnt lgkmcnt(8)
	v_mfma_f32_32x32x16_bf16 v[48:63], v[80:83], v[216:219], v[48:63]
	v_cmp_ge_f32_e32 vcc, s76, v206
	v_mfma_f32_32x32x16_bf16 v[48:63], v[88:91], v[220:223], v[48:63]
	s_cmp_eq_u64 vcc, exec
	v_mfma_f32_32x32x16_bf16 v[48:63], v[84:87], v[224:227], v[48:63]
	v_mfma_f32_32x32x16_bf16 v[48:63], v[92:95], v[228:231], v[48:63]
	s_cbranch_scc0 .LBB0_187
	v_mov_b32_e32 v213, 1.0
	s_mov_b64 vcc, 0
; #define SBAR() __builtin_amdgcn_sched_barrier(0)
; #define VRD8(D0, L0, H0, L1, H1, L2, H2, L3, H3) do { L0 = tr_read<v_rd_off(D0, 0, 0)>(vb); H0 = tr_read<v_rd_off(D0, 0, 1)>(vb); L1 = tr_read<v_rd_off(D0, 1, 0)>(vb); H1 = tr_read<v_rd_off(D0, 1, 1)>(vb); \
;     L2 = tr_read<v_rd_off(D0, 2, 0)>(vb); H2 = tr_read<v_rd_off(D0, 2, 1)>(vb); L3 = tr_read<v_rd_off(D0, 3, 0)>(vb); H3 = tr_read<v_rd_off(D0, 3, 1)>(vb); } while (0)
; #define MMA4(OD, L0, H0, L1, H1, L2, H2, L3, H3) do { OD = __builtin_amdgcn_mfma_f32_32x32x16_bf16(pa0, PK(L0, H0), OD, 0, 0, 0); OD = __builtin_amdgcn_mfma_f32_32x32x16_bf16(pa1, PK(L1, H1), OD, 0, 0, 0); \
;     OD = __builtin_amdgcn_mfma_f32_32x32x16_bf16(pa2, PK(L2, H2), OD, 0, 0, 0); OD = __builtin_amdgcn_mfma_f32_32x32x16_bf16(pa3, PK(L3, H3), OD, 0, 0, 0); } while (0)
; __device__ __forceinline__ void pv_partial(f32x16* o, int vb, bf16x8 pa0, bf16x8 pa1, bf16x8 pa2, bf16x8 pa3, f32x16& p0, f32x16& p1, float& m_ref, f32x16& negm, float& alpha) {
;     ...
;   VRD8(3, b0, b1, b2, b3, b4, b5, b6, b7);
;   asm volatile("s_waitcnt lgkmcnt(8)" ::: "memory"); SBAR();
;   MMA4(o[2], a0, a1, a2, a3, a4, a5, a6, a7);
; #pragma unroll
;   for (int r = 0; r < 8; ++r) p0[r] = __builtin_amdgcn_exp2f(p0[r]);
;   SBAR();
;   asm volatile("s_waitcnt lgkmcnt(0)" ::: "memory"); SBAR();
;   MMA4(o[3], b0, b1, b2, b3, b4, b5, b6, b7);
; template <int MODE, int ORD> ...
;     ...
;   float bL, bR, be_cur = 0.f; f32x16 negm;
; #pragma unroll
;   for (int r = 0; r < 16; ++r) negm[r] = -m_reg;
.LBB0_170:
	ds_read_b64_tr_b16 v[216:217], v201 offset:0x600
	ds_read_b64_tr_b16 v[218:219], v201 offset:0xe00
	ds_read_b64_tr_b16 v[220:221], v201 offset:0x1600
	ds_read_b64_tr_b16 v[222:223], v201 offset:0x1e00
	ds_read_b64_tr_b16 v[224:225], v201 offset:0x2600
	ds_read_b64_tr_b16 v[226:227], v201 offset:0x2e00
	ds_read_b64_tr_b16 v[228:229], v201 offset:0x3600
	ds_read_b64_tr_b16 v[230:231], v201 offset:0x3e00
	s_waitcnt lgkmcnt(8)
	v_mfma_f32_32x32x16_bf16 v[32:47], v[80:83], v[172:175], v[32:47]
	v_mfma_f32_32x32x16_bf16 v[32:47], v[88:91], v[168:171], v[32:47]
	v_mfma_f32_32x32x16_bf16 v[32:47], v[84:87], v[164:167], v[32:47]
	v_mfma_f32_32x32x16_bf16 v[32:47], v[92:95], v[160:163], v[32:47]
	s_waitcnt lgkmcnt(0)
	v_mfma_f32_32x32x16_bf16 v[16:31], v[80:83], v[216:219], v[16:31]
	v_mfma_f32_32x32x16_bf16 v[16:31], v[88:91], v[220:223], v[16:31]
	v_mfma_f32_32x32x16_bf16 v[16:31], v[84:87], v[224:227], v[16:31]
	v_mfma_f32_32x32x16_bf16 v[16:31], v[92:95], v[228:231], v[16:31]
	s_cbranch_vccz .LBB0_174
	s_and_saveexec_b64 s[10:11], s[0:1]
	ds_write_b32 v186, v213 offset:128
	s_or_b64 exec, exec, s[10:11]
	s_waitcnt lgkmcnt(0)
	v_add_u32_e32 v92, s49, v204
	ds_read_b128 v[80:83], v92 offset:224
	ds_read_b128 v[84:87], v92 offset:192
	ds_read_b128 v[88:91], v92 offset:160
	ds_read_b128 v[92:95], v92 offset:128
	s_waitcnt lgkmcnt(3)
	v_pk_mul_f32 v[12:13], v[12:13], v[80:81]
	s_waitcnt lgkmcnt(2)
	v_pk_mul_f32 v[8:9], v[8:9], v[84:85]
	s_waitcnt lgkmcnt(1)
	v_pk_mul_f32 v[4:5], v[4:5], v[88:89]
	v_pk_mul_f32 v[14:15], v[14:15], v[82:83]
	v_pk_mul_f32 v[10:11], v[10:11], v[86:87]
	v_pk_mul_f32 v[6:7], v[6:7], v[90:91]
	s_waitcnt lgkmcnt(0)
	v_pk_mul_f32 v[2:3], v[2:3], v[94:95]
	v_pk_mul_f32 v[0:1], v[0:1], v[92:93]
	v_pk_mul_f32 v[60:61], v[60:61], v[80:81]
	v_pk_mul_f32 v[56:57], v[56:57], v[84:85]
	v_pk_mul_f32 v[52:53], v[52:53], v[88:89]
	v_pk_mul_f32 v[62:63], v[62:63], v[82:83]
	v_pk_mul_f32 v[58:59], v[58:59], v[86:87]
	v_pk_mul_f32 v[54:55], v[54:55], v[90:91]
	v_pk_mul_f32 v[50:51], v[50:51], v[94:95]
	v_pk_mul_f32 v[48:49], v[48:49], v[92:93]
	v_pk_mul_f32 v[44:45], v[44:45], v[80:81]
	v_pk_mul_f32 v[40:41], v[40:41], v[84:85]
	v_pk_mul_f32 v[36:37], v[36:37], v[88:89]
	v_pk_mul_f32 v[46:47], v[46:47], v[82:83]
	v_pk_mul_f32 v[42:43], v[42:43], v[86:87]
	v_pk_mul_f32 v[38:39], v[38:39], v[90:91]
	v_pk_mul_f32 v[34:35], v[34:35], v[94:95]
	v_pk_mul_f32 v[32:33], v[32:33], v[92:93]
	v_pk_mul_f32 v[28:29], v[28:29], v[80:81]
	v_pk_mul_f32 v[24:25], v[24:25], v[84:85]
	v_pk_mul_f32 v[20:21], v[20:21], v[88:89]
	v_pk_mul_f32 v[30:31], v[30:31], v[82:83]
	v_pk_mul_f32 v[26:27], v[26:27], v[86:87]
	v_pk_mul_f32 v[22:23], v[22:23], v[90:91]
	v_pk_mul_f32 v[18:19], v[18:19], v[94:95]
	v_pk_mul_f32 v[16:17], v[16:17], v[92:93]
.LBB0_174:
	s_addk_i32 s56, 0x80
	s_waitcnt vmcnt(0) lgkmcnt(0)
	s_barrier
	s_lshl_b32 m0, s62, 11
	s_add_i32 m0, m0, s43
	s_nop 0
	global_load_lds_dwordx4 v236, s[100:101]
	global_load_lds_dwordx4 v237, s[100:101] offset:1024
	s_addk_i32 m0, 0x4000
	s_nop 0
	global_load_lds_dwordx4 v234, s[100:101]
	global_load_lds_dwordx4 v235, s[100:101] offset:1024
	s_add_u32 s100, s100, 0x90000
	s_addc_u32 s101, s101, 0
	s_addk_i32 s78, 0xbf
	s_cmpk_gt_i32 s78, 0xff80
	s_cselect_b64 s[10:11], -1, 0
	s_cmp_lt_u32 s56, s19
	s_cselect_b64 s[80:81], -1, 0
	s_and_b64 s[10:11], s[10:11], s[80:81]
	s_cmpk_lt_i32 s78, 0xff81
	s_cselect_b64 vcc, -1, 0
	v_cndmask_b32_e32 v80, v200, v195, vcc
	v_cndmask_b32_e64 v214, v80, 0, s[10:11]
	v_cmp_eq_f32_e32 vcc, v214, v215
	s_cbranch_vccnz .LBB0_176
	v_sub_f32_e32 v80, v214, v215
	v_pk_add_f32 v[78:79], v[80:81], v[78:79] op_sel_hi:[0,1]
	v_pk_add_f32 v[76:77], v[80:81], v[76:77] op_sel_hi:[0,1]
	v_pk_add_f32 v[74:75], v[80:81], v[74:75] op_sel_hi:[0,1]
	v_pk_add_f32 v[72:73], v[80:81], v[72:73] op_sel_hi:[0,1]
	v_pk_add_f32 v[70:71], v[80:81], v[70:71] op_sel_hi:[0,1]
	v_pk_add_f32 v[68:69], v[80:81], v[68:69] op_sel_hi:[0,1]
	v_pk_add_f32 v[66:67], v[80:81], v[66:67] op_sel_hi:[0,1]
	v_pk_add_f32 v[64:65], v[80:81], v[64:65] op_sel_hi:[0,1]
	s_branch .LBB0_177

; __device__ __forceinline__ void finishSM(f32x16& p0, f32x16& p1, float alpha, float& l_reg, bf16x8& pa0, bf16x8& pa1, bf16x8& pa2, bf16x8& pa3) {
; #pragma unroll
;   for (int r = 0; r < 16; ++r) p1[r] = __builtin_amdgcn_exp2f(p1[r]);
;   float ps = 0;
; #pragma unroll
;   for (int r = 0; r < 16; ++r) ps += p0[r];
; #pragma unroll
;   for (int r = 0; r < 16; ++r) ps += p1[r];
;   { auto rr = __builtin_amdgcn_permlane32_swap(__float_as_uint(ps), __float_as_uint(ps), false, false);
;     ps = __uint_as_float(rr[0]) + __uint_as_float(rr[1]); }
;   l_reg = l_reg * alpha + ps;
;     ...
;   PK4(p0, 0, pa0); PK4(p0, 8, pa1); PK4(p1, 0, pa2); PK4(p1, 8, pa3);
; template <int ND0> __device__ __forceinline__ void qkt(f32x16& p0, f32x16& p1, const char* Ks, const bf16x8* qr, int r32, int hi, int cboff, const f32x16& ci) {
; #pragma unroll
;   for (int d0 = 0; d0 < ND0; ++d0) { int cb = cboff + (d0 * 16 + hi * 8) * 2;
;     bf16x8 b0 = *reinterpret_cast<const bf16x8*>(Ks + KSWZ(r32, cb));
;     bf16x8 b1 = *reinterpret_cast<const bf16x8*>(Ks + KSWZ(32 + r32, cb));
;     if (d0 == 0) { p0 = __builtin_amdgcn_mfma_f32_32x32x16_bf16(b0, qr[0], ci, 0, 0, 0); p1 = __builtin_amdgcn_mfma_f32_32x32x16_bf16(b1, qr[0], ci, 0, 0, 0); }
;     else { p0 = __builtin_amdgcn_mfma_f32_32x32x16_bf16(b0, qr[d0], p0, 0, 0, 0); p1 = __builtin_amdgcn_mfma_f32_32x32x16_bf16(b1, qr[d0], p1, 0, 0, 0); } }
; }
.LBB0_177:
	v_exp_f32_e32 v168, v112
	v_exp_f32_e32 v169, v113
	v_exp_f32_e32 v170, v114
	v_exp_f32_e32 v171, v115
	v_exp_f32_e32 v172, v116
	v_exp_f32_e32 v173, v117
	v_exp_f32_e32 v174, v118
	v_exp_f32_e32 v175, v119
	v_exp_f32_e32 v206, v120
	v_exp_f32_e32 v207, v121
	v_exp_f32_e32 v208, v122
	v_exp_f32_e32 v209, v123
	v_exp_f32_e32 v217, v124
	v_exp_f32_e32 v218, v125
	v_exp_f32_e32 v219, v126
	v_exp_f32_e32 v220, v127
	v_add_u32_e32 v80, s18, v188
	ds_read_b128 v[160:163], v80 offset:24576
	ds_read_b128 v[80:83], v80 offset:16384
	v_add_u32_e32 v164, s18, v196
	v_exp_f32_e32 v96, v96
	v_exp_f32_e32 v97, v97
	v_exp_f32_e32 v98, v98
	s_waitcnt lgkmcnt(0)
	v_mfma_f32_32x32x16_bf16 v[112:127], v[80:83], v[128:131], v[64:79]
	v_exp_f32_e32 v99, v99
	v_exp_f32_e32 v100, v100
	v_exp_f32_e32 v101, v101
	v_exp_f32_e32 v102, v102
	v_exp_f32_e32 v103, v103
	v_mfma_f32_32x32x16_bf16 v[80:95], v[160:163], v[128:131], v[64:79]
	ds_read_b128 v[160:163], v164 offset:24576
	ds_read_b128 v[164:167], v164 offset:16384
	s_waitcnt lgkmcnt(1)
	v_mfma_f32_32x32x16_bf16 v[80:95], v[160:163], v[132:135], v[80:95]
	s_waitcnt lgkmcnt(0)
	v_mfma_f32_32x32x16_bf16 v[112:127], v[164:167], v[132:135], v[112:127]
	v_add_u32_e32 v164, s18, v190
	ds_read_b128 v[160:163], v164 offset:24576
	ds_read_b128 v[164:167], v164 offset:16384
	s_waitcnt lgkmcnt(1)
	v_mfma_f32_32x32x16_bf16 v[80:95], v[160:163], v[136:139], v[80:95]
	s_waitcnt lgkmcnt(0)
	v_mfma_f32_32x32x16_bf16 v[112:127], v[164:167], v[136:139], v[112:127]
	v_add_u32_e32 v164, s18, v189
	ds_read_b128 v[160:163], v164 offset:24576
	ds_read_b128 v[164:167], v164 offset:16384
	s_waitcnt lgkmcnt(1)
	v_mfma_f32_32x32x16_bf16 v[80:95], v[160:163], v[140:143], v[80:95]
	v_exp_f32_e32 v160, v104
	v_pk_add_f32 v[144:145], v[168:169], v[170:171]
	v_pk_add_f32 v[144:145], v[144:145], v[172:173]
	v_pk_add_f32 v[144:145], v[144:145], v[174:175]
	v_pk_add_f32 v[144:145], v[144:145], v[206:207]
	v_pk_add_f32 v[144:145], v[144:145], v[208:209]
	v_pk_add_f32 v[144:145], v[144:145], v[218:219]
	v_pk_add_f32 v[144:145], v[144:145], v[96:97]
	v_pk_add_f32 v[144:145], v[144:145], v[98:99]
	v_pk_add_f32 v[144:145], v[144:145], v[100:101]
	v_exp_f32_e32 v161, v105
	v_pk_add_f32 v[144:145], v[144:145], v[102:103]
	v_exp_f32_e32 v162, v106
	v_add_f32_e32 v104, v217, v220
	v_exp_f32_e32 v163, v107
	s_waitcnt lgkmcnt(0)
	v_mfma_f32_32x32x16_bf16 v[112:127], v[164:167], v[140:143], v[112:127]
	v_exp_f32_e32 v164, v108
	v_exp_f32_e32 v165, v109
	v_exp_f32_e32 v166, v110
	v_exp_f32_e32 v167, v111
	v_pk_add_f32 v[144:145], v[144:145], v[160:161]
	v_pk_add_f32 v[144:145], v[144:145], v[162:163]
	v_pk_add_f32 v[144:145], v[144:145], v[164:165]
	v_pk_add_f32 v[144:145], v[144:145], v[166:167]
	v_add_f32_e32 v104, v144, v104
	v_add_f32_e32 v215, v145, v104
	v_cvt_pk_bf16_f32 v104, v168, v169
	v_cvt_pk_bf16_f32 v105, v170, v171
	v_cvt_pk_bf16_f32 v106, v172, v173
	v_cvt_pk_bf16_f32 v107, v174, v175
	v_cvt_pk_bf16_f32 v108, v206, v207
	v_cvt_pk_bf16_f32 v109, v208, v209
	v_cvt_pk_bf16_f32 v110, v217, v218
	v_cvt_pk_bf16_f32 v111, v219, v220
	v_cvt_pk_bf16_f32 v96, v96, v97
	v_cvt_pk_bf16_f32 v97, v98, v99
	v_cvt_pk_bf16_f32 v98, v100, v101
	v_cvt_pk_bf16_f32 v99, v102, v103
	v_cvt_pk_bf16_f32 v100, v160, v161
	v_cvt_pk_bf16_f32 v101, v162, v163
	v_cvt_pk_bf16_f32 v102, v164, v165
	v_cvt_pk_bf16_f32 v103, v166, v167
	s_andn2_b64 vcc, exec, s[10:11]
	s_cbranch_vccnz .LBB0_179
; #define SBAR() __builtin_amdgcn_sched_barrier(0)
; __device__ __forceinline__ float max3f(float a, float b, float c) { float r; asm("v_max3_f32 %0, %1, %2, %3" : "=v"(r) : "v"(a), "v"(b), "v"(c)); return r; }
; #define VRD8(D0, L0, H0, L1, H1, L2, H2, L3, H3) do { L0 = tr_read<v_rd_off(D0, 0, 0)>(vb); H0 = tr_read<v_rd_off(D0, 0, 1)>(vb); L1 = tr_read<v_rd_off(D0, 1, 0)>(vb); H1 = tr_read<v_rd_off(D0, 1, 1)>(vb); \
;     L2 = tr_read<v_rd_off(D0, 2, 0)>(vb); H2 = tr_read<v_rd_off(D0, 2, 1)>(vb); L3 = tr_read<v_rd_off(D0, 3, 0)>(vb); H3 = tr_read<v_rd_off(D0, 3, 1)>(vb); } while (0)
; #define MMA4(OD, L0, H0, L1, H1, L2, H2, L3, H3) do { OD = __builtin_amdgcn_mfma_f32_32x32x16_bf16(pa0, PK(L0, H0), OD, 0, 0, 0); OD = __builtin_amdgcn_mfma_f32_32x32x16_bf16(pa1, PK(L1, H1), OD, 0, 0, 0); \
;     OD = __builtin_amdgcn_mfma_f32_32x32x16_bf16(pa2, PK(L2, H2), OD, 0, 0, 0); OD = __builtin_amdgcn_mfma_f32_32x32x16_bf16(pa3, PK(L3, H3), OD, 0, 0, 0); } while (0)
; __device__ __forceinline__ void pv_partial(f32x16* o, int vb, bf16x8 pa0, bf16x8 pa1, bf16x8 pa2, bf16x8 pa3, f32x16& p0, f32x16& p1, float& m_ref, f32x16& negm, float& alpha) {
;   s16x4 a0, a1, a2, a3, a4, a5, a6, a7, b0, b1, b2, b3, b4, b5, b6, b7;
;   VRD8(0, a0, a1, a2, a3, a4, a5, a6, a7);
;   VRD8(1, b0, b1, b2, b3, b4, b5, b6, b7);
;   asm volatile("s_waitcnt lgkmcnt(8)" ::: "memory"); SBAR();
;   MMA4(o[0], a0, a1, a2, a3, a4, a5, a6, a7);
;   float pmax = max3f(p0[0], p0[1], p1[0]), pmb = max3f(p0[2], p0[3], p1[1]);
;   pmax = max3f(pmax, p1[2], p1[3]);
; #pragma unroll
;   for (int r = 4; r < 16; r += 4) { pmax = max3f(pmax, p0[r], p0[r + 1]); pmb = max3f(pmb, p0[r + 2], p0[r + 3]); pmax = max3f(pmax, p1[r], p1[r + 1]); pmb = max3f(pmb, p1[r + 2], p1[r + 3]); }
;   pmax = max3f(pmax, pmb, pmb);
;   SBAR();
;   VRD8(2, a0, a1, a2, a3, a4, a5, a6, a7);
;   asm volatile("s_waitcnt lgkmcnt(8)" ::: "memory"); SBAR();
;   MMA4(o[1], b0, b1, b2, b3, b4, b5, b6, b7);
;   { auto rr = __builtin_amdgcn_permlane32_swap(__float_as_uint(pmax), __float_as_uint(pmax), false, false);
;     pmax = fmaxf(__uint_as_float(rr[0]), __uint_as_float(rr[1])); }
;   alpha = 1.f;
;   if (!__builtin_expect(__all(pmax <= THR), 1)) {
	v_add_u32_e32 v160, 0x100, v212
	v_med3_i32 v161, v160, 0, v249
	v_med3_i32 v160, v160, s75, v250
	v_lshl_add_u32 v162, v160, 2, s69
	v_add_u32_e32 v160, 0x101, v212
	v_med3_i32 v163, v160, 0, v249
	v_med3_i32 v160, v160, s75, v250
	v_lshl_add_u32 v164, v160, 2, s69
	v_add_u32_e32 v160, 0x102, v212
	v_med3_i32 v165, v160, 0, v249
	v_med3_i32 v160, v160, s75, v250
	v_lshl_add_u32 v166, v160, 2, s69
	v_add_u32_e32 v160, 0x103, v212
	v_med3_i32 v167, v160, 0, v249
	v_med3_i32 v160, v160, s75, v250
	v_lshl_add_u32 v161, v161, 2, s69
	v_lshl_add_u32 v163, v163, 2, s69
	v_lshl_add_u32 v165, v165, 2, s69
	v_lshl_add_u32 v167, v167, 2, s69
	v_lshl_add_u32 v168, v160, 2, s69
	ds_read_b32 v160, v161
	ds_read_b32 v162, v162 offset:128
	ds_read_b32 v161, v163
	ds_read_b32 v163, v164 offset:128
	ds_read_b32 v164, v165
	ds_read_b32 v166, v166 offset:128
	ds_read_b32 v165, v167
	ds_read_b32 v167, v168 offset:128
	v_add_u32_e32 v168, 0x108, v212
	v_med3_i32 v169, v168, 0, v249
	v_med3_i32 v168, v168, s75, v250
	v_lshl_add_u32 v170, v168, 2, s69
	v_add_u32_e32 v168, 0x109, v212
	v_med3_i32 v171, v168, 0, v249
	v_med3_i32 v168, v168, s75, v250
	v_lshl_add_u32 v172, v168, 2, s69
	v_add_u32_e32 v168, 0x10a, v212
	v_med3_i32 v173, v168, 0, v249
	v_med3_i32 v168, v168, s75, v250
	v_lshl_add_u32 v174, v168, 2, s69
	v_add_u32_e32 v168, 0x10b, v212
	v_med3_i32 v175, v168, 0, v249
	v_med3_i32 v168, v168, s75, v250
	v_lshl_add_u32 v169, v169, 2, s69
	v_lshl_add_u32 v171, v171, 2, s69
	v_lshl_add_u32 v173, v173, 2, s69
	v_lshl_add_u32 v175, v175, 2, s69
	v_lshl_add_u32 v206, v168, 2, s69
	ds_read_b32 v168, v169
	ds_read_b32 v170, v170 offset:128
	ds_read_b32 v169, v171
	ds_read_b32 v171, v172 offset:128
	ds_read_b32 v172, v173
	ds_read_b32 v174, v174 offset:128
	ds_read_b32 v173, v175
	ds_read_b32 v175, v206 offset:128
	v_add_u32_e32 v206, 0x110, v212
	v_med3_i32 v207, v206, 0, v249
	v_med3_i32 v206, v206, s75, v250
	v_lshl_add_u32 v208, v206, 2, s69
	v_add_u32_e32 v206, 0x111, v212
	v_med3_i32 v209, v206, 0, v249
	v_med3_i32 v206, v206, s75, v250
	v_lshl_add_u32 v217, v206, 2, s69
	v_add_u32_e32 v206, 0x112, v212
	v_med3_i32 v218, v206, 0, v249
	v_med3_i32 v206, v206, s75, v250
	v_lshl_add_u32 v219, v206, 2, s69
	v_add_u32_e32 v206, 0x113, v212
	v_add_u32_e32 v223, 0x119, v212
	v_med3_i32 v220, v206, 0, v249
	v_med3_i32 v224, v223, 0, v249
	v_med3_i32 v223, v223, s75, v250
	v_lshl_add_u32 v207, v207, 2, s69
	v_lshl_add_u32 v209, v209, 2, s69
	v_lshl_add_u32 v218, v218, 2, s69
	v_med3_i32 v206, v206, s75, v250
	v_lshl_add_u32 v221, v220, 2, s69
	v_lshl_add_u32 v230, v223, 2, s69
	v_add_u32_e32 v223, 0x11a, v212
	v_lshl_add_u32 v222, v206, 2, s69
	ds_read_b32 v206, v207
	ds_read_b32 v208, v208 offset:128
	ds_read_b32 v207, v209
	ds_read_b32 v209, v217 offset:128
	ds_read_b32 v218, v218
	ds_read_b32 v220, v219 offset:128
	ds_read_b32 v219, v221
	ds_read_b32 v221, v222 offset:128
	v_add_u32_e32 v217, 0x118, v212
	v_lshl_add_u32 v225, v224, 2, s69
	v_med3_i32 v224, v223, 0, v249
	v_med3_i32 v223, v223, s75, v250
	v_add_u32_e32 v212, 0x11b, v212
	v_med3_i32 v222, v217, 0, v249
	v_lshl_add_u32 v228, v223, 2, s69
	v_med3_i32 v223, v212, 0, v249
	v_med3_i32 v217, v217, s75, v250
	v_lshl_add_u32 v222, v222, 2, s69
	v_lshl_add_u32 v226, v224, 2, s69
	v_med3_i32 v212, v212, s75, v250
	v_lshl_add_u32 v223, v223, 2, s69
	v_lshl_add_u32 v217, v217, 2, s69
	v_lshl_add_u32 v212, v212, 2, s69
	ds_read_b32 v222, v222
	ds_read_b32 v224, v217 offset:128
	ds_read_b32 v226, v226
	ds_read_b32 v227, v223
	ds_read_b32 v223, v225
	ds_read_b32 v229, v212 offset:128
	ds_read_b32 v228, v228 offset:128
	ds_read_b32 v225, v230 offset:128
	s_waitcnt lgkmcnt(4)
	v_pk_add_f32 v[126:127], v[126:127], v[226:227]
	s_waitcnt lgkmcnt(3)
	v_pk_add_f32 v[124:125], v[124:125], v[222:223]
	v_pk_add_f32 v[122:123], v[122:123], v[218:219]
	v_pk_add_f32 v[120:121], v[120:121], v[206:207]
	v_pk_add_f32 v[118:119], v[118:119], v[172:173]
	v_pk_add_f32 v[116:117], v[116:117], v[168:169]
	v_pk_add_f32 v[114:115], v[114:115], v[164:165]
	v_pk_add_f32 v[112:113], v[112:113], v[160:161]
	s_waitcnt lgkmcnt(1)
	v_pk_add_f32 v[94:95], v[94:95], v[228:229]
	s_waitcnt lgkmcnt(0)
	v_pk_add_f32 v[92:93], v[92:93], v[224:225]
	v_pk_add_f32 v[90:91], v[90:91], v[220:221]
	v_pk_add_f32 v[88:89], v[88:89], v[208:209]
	v_pk_add_f32 v[86:87], v[86:87], v[174:175]
	v_pk_add_f32 v[84:85], v[84:85], v[170:171]
	v_pk_add_f32 v[82:83], v[82:83], v[166:167]
	v_pk_add_f32 v[80:81], v[80:81], v[162:163]
.LBB0_179:
	v_add_u32_e32 v217, s68, v199
	ds_read_b64_tr_b16 v[160:161], v217 offset:0
	ds_read_b64_tr_b16 v[162:163], v217 offset:0x800
	ds_read_b64_tr_b16 v[164:165], v217 offset:0x1000
	ds_read_b64_tr_b16 v[166:167], v217 offset:0x1800
	ds_read_b64_tr_b16 v[168:169], v217 offset:0x2000
	ds_read_b64_tr_b16 v[170:171], v217 offset:0x2800
	ds_read_b64_tr_b16 v[172:173], v217 offset:0x3000
	ds_read_b64_tr_b16 v[174:175], v217 offset:0x3800
	ds_read_b64_tr_b16 v[218:219], v217 offset:0x200
	ds_read_b64_tr_b16 v[220:221], v217 offset:0xa00
	ds_read_b64_tr_b16 v[222:223], v217 offset:0x1200
	ds_read_b64_tr_b16 v[224:225], v217 offset:0x1a00
	ds_read_b64_tr_b16 v[226:227], v217 offset:0x2200
	ds_read_b64_tr_b16 v[228:229], v217 offset:0x2a00
	ds_read_b64_tr_b16 v[230:231], v217 offset:0x3200
	ds_read_b64_tr_b16 v[232:233], v217 offset:0x3a00
	s_waitcnt lgkmcnt(8)
	v_mfma_f32_32x32x16_bf16 v[0:15], v[104:107], v[160:163], v[0:15]
	v_max3_f32 v160, v112, v113, v80
	v_max3_f32 v161, v114, v115, v81
	v_max3_f32 v160, v160, v82, v83
	v_max3_f32 v161, v161, v118, v119
	v_max3_f32 v160, v160, v116, v117
	v_mfma_f32_32x32x16_bf16 v[0:15], v[108:111], v[164:167], v[0:15]
	v_max3_f32 v160, v160, v84, v85
	v_max3_f32 v161, v161, v86, v87
	v_max3_f32 v160, v160, v120, v121
	v_max3_f32 v161, v161, v122, v123
	v_max3_f32 v160, v160, v88, v89
	v_mfma_f32_32x32x16_bf16 v[0:15], v[96:99], v[168:171], v[0:15]
	v_max3_f32 v161, v161, v90, v91
	v_max3_f32 v160, v160, v124, v125
	v_max3_f32 v161, v161, v126, v127
	v_max3_f32 v160, v160, v92, v93
	v_max3_f32 v161, v161, v94, v95
	v_mfma_f32_32x32x16_bf16 v[0:15], v[100:103], v[172:175], v[0:15]
	v_max3_f32 v206, v160, v161, v161
	ds_read_b64_tr_b16 v[172:173], v217 offset:0x400
	ds_read_b64_tr_b16 v[174:175], v217 offset:0xc00
	ds_read_b64_tr_b16 v[168:169], v217 offset:0x1400
	ds_read_b64_tr_b16 v[170:171], v217 offset:0x1c00
	ds_read_b64_tr_b16 v[164:165], v217 offset:0x2400
	ds_read_b64_tr_b16 v[166:167], v217 offset:0x2c00
	ds_read_b64_tr_b16 v[160:161], v217 offset:0x3400
	ds_read_b64_tr_b16 v[162:163], v217 offset:0x3c00
	s_waitcnt lgkmcnt(8)
	v_mfma_f32_32x32x16_bf16 v[48:63], v[104:107], v[218:221], v[48:63]
	v_cmp_ge_f32_e32 vcc, s76, v206
	v_mfma_f32_32x32x16_bf16 v[48:63], v[108:111], v[222:225], v[48:63]
	s_cmp_eq_u64 vcc, exec
	v_mfma_f32_32x32x16_bf16 v[48:63], v[96:99], v[226:229], v[48:63]
	v_mfma_f32_32x32x16_bf16 v[48:63], v[100:103], v[230:233], v[48:63]
	s_cbranch_scc0 .LBB0_188
	v_mov_b32_e32 v212, 1.0
	s_mov_b64 vcc, 0

.LBB0_185:
	v_exp_f32_e32 v173, v112
	v_exp_f32_e32 v175, v113
	v_exp_f32_e32 v171, v114
	v_exp_f32_e32 v174, v115
	v_exp_f32_e32 v169, v116
	v_exp_f32_e32 v172, v117
	v_exp_f32_e32 v168, v118
	v_exp_f32_e32 v170, v119
	v_exp_f32_e32 v165, v120
	v_exp_f32_e32 v167, v121
	v_exp_f32_e32 v163, v122
	v_exp_f32_e32 v166, v123
	v_exp_f32_e32 v161, v124
	v_exp_f32_e32 v164, v125
	v_exp_f32_e32 v160, v126
	v_exp_f32_e32 v162, v127
	v_fma_f32 v96, v203, v187, v210
	s_add_i32 s57, s57, 2
	s_mov_b64 s[10:11], 0x120000
	v_fma_f32 v187, v96, v213, v215
	s_cmp_ge_u32 s57, s67
	v_lshl_add_u64 v[176:177], v[176:177], 0, s[10:11]
	s_waitcnt vmcnt(0) lgkmcnt(0)
	s_barrier
	s_cbranch_scc1 .LBB0_189
	s_mov_b32 s10, s18
	s_mov_b32 s18, s68
	v_mov_b32_e32 v203, v212
	s_branch .LBB0_163
